# combo22 + attention epilogue Y stores with the streaming (nt) policy
# speedup vs baseline: 1.0010x; 1.0010x over previous
.LBB0_1619:
	s_or_b64 exec, exec, s[48:49]
	v_mov_b32_e32 v4, v222
	s_waitcnt lgkmcnt(0)
	v_mov_b32_e32 v40, v139
	v_lshlrev_b32_e32 v0, 3, v4
	v_and_b32_e32 v138, 0x78, v0
	v_ashrrev_i32_e32 v8, 4, v4
	v_lshlrev_b32_e32 v5, 2, v138
	v_ashrrev_i32_e32 v9, 31, v8
	global_load_dwordx4 v[0:3], v5, s[26:27]
	global_load_dwordx4 v[14:17], v5, s[26:27] offset:16
	v_mov_b32_e32 v5, v139
	v_lshlrev_b32_e32 v4, 1, v138
	v_lshl_add_u64 v[6:7], v[64:65], 0, v[8:9]
	v_lshl_add_u64 v[10:11], s[28:29], 0, v[4:5]
	v_lshlrev_b64 v[6:7], 12, v[6:7]
	v_lshl_add_u64 v[12:13], v[10:11], 0, v[6:7]
	global_load_dwordx4 v[18:21], v[12:13], off nt
	v_add_u32_e32 v12, 4, v8
	v_ashrrev_i32_e32 v13, 31, v12
	v_lshl_add_u64 v[22:23], v[64:65], 0, v[12:13]
	v_lshlrev_b64 v[38:39], 12, v[22:23]
	v_lshl_add_u64 v[22:23], v[10:11], 0, v[38:39]
	global_load_dwordx4 v[22:25], v[22:23], off nt
	v_add_u32_e32 v26, 8, v8
	v_add_u32_e32 v28, 12, v8
	v_ashrrev_i32_e32 v27, 31, v26
	v_ashrrev_i32_e32 v29, 31, v28
	v_add_u32_e32 v46, s56, v4
	v_lshl_add_u64 v[4:5], v[64:65], 0, v[26:27]
	v_lshl_add_u64 v[30:31], v[64:65], 0, v[28:29]
	v_lshl_add_u32 v29, v12, 8, v46
	v_lshlrev_b64 v[42:43], 12, v[4:5]
	v_lshlrev_b64 v[12:13], 12, v[30:31]
	v_lshl_add_u32 v9, v8, 8, v46
	v_lshl_add_u32 v47, v26, 8, v46
	v_lshl_add_u64 v[26:27], s[30:31], 0, v[6:7]
	v_lshl_add_u64 v[30:31], v[10:11], 0, v[42:43]
	v_lshl_add_u64 v[34:35], v[10:11], 0, v[12:13]
	v_lshl_add_u32 v48, v28, 8, v46
	ds_read_b128 v[4:7], v9
	v_lshl_add_u64 v[44:45], v[26:27], 0, v[138:139]
	ds_read_b128 v[26:29], v29
	global_load_dwordx4 v[30:33], v[30:31], off nt
	s_nop 0
	global_load_dwordx4 v[34:37], v[34:35], off nt
	v_add_u32_e32 v232, 16, v8
	v_ashrrev_i32_e32 v233, 31, v232
	v_lshl_add_u64 v[232:233], v[64:65], 0, v[232:233]
	v_lshlrev_b64 v[232:233], 12, v[232:233]
	v_lshl_add_u64 v[232:233], v[10:11], 0, v[232:233]
	global_load_dwordx4 v[236:239], v[232:233], off nt
	v_add_u32_e32 v232, 20, v8
	v_ashrrev_i32_e32 v233, 31, v232
	v_lshl_add_u64 v[232:233], v[64:65], 0, v[232:233]
	v_lshlrev_b64 v[232:233], 12, v[232:233]
	v_lshl_add_u64 v[232:233], v[10:11], 0, v[232:233]
	global_load_dwordx4 v[240:243], v[232:233], off nt
	v_add_u32_e32 v232, 24, v8
	v_ashrrev_i32_e32 v233, 31, v232
	v_lshl_add_u64 v[232:233], v[64:65], 0, v[232:233]
	v_lshlrev_b64 v[232:233], 12, v[232:233]
	v_lshl_add_u64 v[232:233], v[10:11], 0, v[232:233]
	global_load_dwordx4 v[244:247], v[232:233], off nt
	v_add_u32_e32 v232, 28, v8
	v_ashrrev_i32_e32 v233, 31, v232
	v_lshl_add_u64 v[232:233], v[64:65], 0, v[232:233]
	v_lshlrev_b64 v[232:233], 12, v[232:233]
	v_lshl_add_u64 v[232:233], v[10:11], 0, v[232:233]
	global_load_dwordx4 v[248:251], v[232:233], off nt
	v_mov_b32_e32 v41, v139
	s_waitcnt lgkmcnt(1)
	v_cvt_f32_f16_sdwa v49, v4 dst_sel:DWORD dst_unused:UNUSED_PAD src0_sel:WORD_1
	v_cvt_f32_f16_sdwa v51, v5 dst_sel:DWORD dst_unused:UNUSED_PAD src0_sel:WORD_1
	v_cvt_f32_f16_sdwa v53, v6 dst_sel:DWORD dst_unused:UNUSED_PAD src0_sel:WORD_1
	v_cvt_f32_f16_sdwa v55, v7 dst_sel:DWORD dst_unused:UNUSED_PAD src0_sel:WORD_1
	v_cvt_f32_f16_e32 v9, v4
	v_cvt_f32_f16_e32 v50, v5
	v_cvt_f32_f16_e32 v52, v6
	v_cvt_f32_f16_e32 v54, v7
	s_waitcnt lgkmcnt(0)
	v_cvt_f32_f16_e32 v56, v26
	v_cvt_f32_f16_sdwa v26, v26 dst_sel:DWORD dst_unused:UNUSED_PAD src0_sel:WORD_1
	v_lshl_add_u64 v[12:13], s[30:31], 0, v[12:13]
	v_lshl_add_u64 v[12:13], v[12:13], 0, v[138:139]
	s_mov_b64 s[48:49], 0
	s_and_b64 vcc, exec, s[0:1]
	s_waitcnt vmcnt(9)
	v_pk_mul_f32 v[4:5], v[2:3], s[16:17] op_sel_hi:[1,0]
	v_pk_mul_f32 v[6:7], v[0:1], s[16:17] op_sel_hi:[1,0]
	s_waitcnt vmcnt(8)
	v_pk_mul_f32 v[0:1], v[16:17], s[16:17] op_sel_hi:[1,0]
	v_pk_mul_f32 v[2:3], v[14:15], s[16:17] op_sel_hi:[1,0]
	v_mul_f32_e32 v14, v7, v49
	v_mul_f32_e32 v16, v5, v51
	v_mul_f32_e32 v49, v3, v53
	v_mul_f32_e32 v51, v1, v55
	s_waitcnt vmcnt(7)
	v_cvt_f32_f16_e32 v53, v18
	v_cvt_f32_f16_sdwa v18, v18 dst_sel:DWORD dst_unused:UNUSED_PAD src0_sel:WORD_1
	v_cvt_f32_f16_e32 v55, v20
	v_cvt_f32_f16_sdwa v20, v20 dst_sel:DWORD dst_unused:UNUSED_PAD src0_sel:WORD_1
	v_mul_f32_e32 v9, v6, v9
	v_mul_f32_e32 v17, v2, v52
	v_mul_f32_e32 v15, v4, v50
	v_mul_f32_e32 v50, v0, v54
	v_mul_f32_e32 v52, v6, v56
	v_cvt_f32_f16_e32 v54, v19
	v_cvt_f32_f16_sdwa v19, v19 dst_sel:DWORD dst_unused:UNUSED_PAD src0_sel:WORD_1
	v_cvt_f32_f16_e32 v56, v21
	v_cvt_f32_f16_sdwa v21, v21 dst_sel:DWORD dst_unused:UNUSED_PAD src0_sel:WORD_1
	v_mul_f32_e32 v9, v9, v53
	v_mul_f32_e32 v14, v14, v18
	v_mul_f32_e32 v17, v17, v55
	v_mul_f32_e32 v18, v49, v20
	v_med3_f32 v9, v9, s62, v187
	v_med3_f32 v14, v14, s62, v187
	v_med3_f32 v17, v17, s62, v187
	v_med3_f32 v18, v18, s62, v187
	v_cvt_pk_fp8_f32 v40, v9, v14
	v_cvt_pk_fp8_f32 v41, v17, v18
	v_mul_f32_e32 v15, v15, v54
	v_mul_f32_e32 v16, v16, v19
	v_mul_f32_e32 v19, v50, v56
	v_mul_f32_e32 v20, v51, v21
	v_med3_f32 v15, v15, s62, v187
	v_med3_f32 v16, v16, s62, v187
	v_med3_f32 v9, v19, s62, v187
	v_med3_f32 v14, v20, s62, v187
	v_cvt_pk_fp8_f32 v40, v15, v16 op_sel:[0,0,1]
	v_cvt_pk_fp8_f32 v41, v9, v14 op_sel:[0,0,1]
	s_waitcnt vmcnt(6)
	v_cvt_f32_f16_sdwa v14, v22 dst_sel:DWORD dst_unused:UNUSED_PAD src0_sel:WORD_1
	v_cvt_f32_f16_e32 v16, v27
	v_cvt_f32_f16_e32 v57, v22
	v_cvt_f32_f16_e32 v17, v23
	v_cvt_f32_f16_sdwa v18, v27 dst_sel:DWORD dst_unused:UNUSED_PAD src0_sel:WORD_1
	v_mul_f32_e32 v9, v7, v26
	v_mul_f32_e32 v9, v9, v14
	v_mul_f32_e32 v14, v4, v16
	v_mul_f32_e32 v15, v52, v57
	v_mul_f32_e32 v14, v14, v17
	v_cvt_f32_f16_sdwa v17, v23 dst_sel:DWORD dst_unused:UNUSED_PAD src0_sel:WORD_1
	v_mul_f32_e32 v16, v5, v18
	v_med3_f32 v15, v15, s62, v187
	v_med3_f32 v9, v9, s62, v187
	v_mov_b32_e32 v18, v139
	v_cvt_pk_fp8_f32 v18, v15, v9
	v_mul_f32_e32 v9, v16, v17
	v_med3_f32 v14, v14, s62, v187
	v_med3_f32 v9, v9, s62, v187
	v_cvt_pk_fp8_f32 v18, v14, v9 op_sel:[0,0,1]
	v_cvt_f32_f16_e32 v9, v28
	v_cvt_f32_f16_e32 v14, v24
	v_cvt_f32_f16_sdwa v15, v28 dst_sel:DWORD dst_unused:UNUSED_PAD src0_sel:WORD_1
	v_cvt_f32_f16_sdwa v16, v24 dst_sel:DWORD dst_unused:UNUSED_PAD src0_sel:WORD_1
	v_mul_f32_e32 v9, v2, v9
	v_mul_f32_e32 v9, v9, v14
	v_mul_f32_e32 v14, v3, v15
	v_cvt_f32_f16_e32 v15, v29
	v_mul_f32_e32 v14, v14, v16
	v_cvt_f32_f16_e32 v16, v25
	v_cvt_f32_f16_sdwa v17, v29 dst_sel:DWORD dst_unused:UNUSED_PAD src0_sel:WORD_1
	v_cvt_f32_f16_sdwa v19, v25 dst_sel:DWORD dst_unused:UNUSED_PAD src0_sel:WORD_1
	v_mul_f32_e32 v15, v0, v15
	v_mul_f32_e32 v15, v15, v16
	v_mul_f32_e32 v16, v1, v17
	v_mul_f32_e32 v20, v16, v19
	v_med3_f32 v9, v9, s62, v187
	v_med3_f32 v14, v14, s62, v187
	v_mov_b32_e32 v19, v139
	v_cvt_pk_fp8_f32 v19, v9, v14
	v_med3_f32 v9, v15, s62, v187
	ds_read_b128 v[14:17], v47
	v_med3_f32 v20, v20, s62, v187
	v_cvt_pk_fp8_f32 v19, v9, v20 op_sel:[0,0,1]
	v_lshl_add_u64 v[20:21], s[30:31], 0, v[38:39]
	v_lshl_add_u64 v[20:21], v[20:21], 0, v[138:139]
	s_waitcnt lgkmcnt(0)
	v_cvt_f32_f16_e32 v9, v14
	v_cvt_f32_f16_sdwa v14, v14 dst_sel:DWORD dst_unused:UNUSED_PAD src0_sel:WORD_1
	global_store_dwordx2 v[20:21], v[18:19], off offset:2048 nt
	s_waitcnt vmcnt(6)
	v_cvt_f32_f16_sdwa v18, v30 dst_sel:DWORD dst_unused:UNUSED_PAD src0_sel:WORD_1
	v_cvt_f32_f16_e32 v19, v15
	v_cvt_f32_f16_e32 v22, v30
	v_cvt_f32_f16_e32 v20, v31
	v_mul_f32_e32 v14, v7, v14
	v_mul_f32_e32 v9, v6, v9
	v_cvt_f32_f16_sdwa v15, v15 dst_sel:DWORD dst_unused:UNUSED_PAD src0_sel:WORD_1
	v_mul_f32_e32 v14, v14, v18
	v_mul_f32_e32 v18, v4, v19
	v_mul_f32_e32 v9, v9, v22
	v_mul_f32_e32 v19, v18, v20
	v_cvt_f32_f16_sdwa v20, v31 dst_sel:DWORD dst_unused:UNUSED_PAD src0_sel:WORD_1
	v_med3_f32 v9, v9, s62, v187
	v_med3_f32 v14, v14, s62, v187
	v_mov_b32_e32 v18, v139
	v_cvt_pk_fp8_f32 v18, v9, v14
	v_mul_f32_e32 v15, v5, v15
	v_mul_f32_e32 v9, v15, v20
	v_med3_f32 v14, v19, s62, v187
	v_med3_f32 v9, v9, s62, v187
	v_cvt_pk_fp8_f32 v18, v14, v9 op_sel:[0,0,1]
	v_cvt_f32_f16_e32 v9, v16
	v_cvt_f32_f16_e32 v14, v32
	v_cvt_f32_f16_sdwa v15, v16 dst_sel:DWORD dst_unused:UNUSED_PAD src0_sel:WORD_1
	v_cvt_f32_f16_sdwa v16, v32 dst_sel:DWORD dst_unused:UNUSED_PAD src0_sel:WORD_1
	v_mul_f32_e32 v9, v2, v9
	v_mul_f32_e32 v9, v9, v14
	v_mul_f32_e32 v14, v3, v15
	v_cvt_f32_f16_e32 v15, v17
	v_mul_f32_e32 v14, v14, v16
	v_cvt_f32_f16_e32 v16, v33
	v_cvt_f32_f16_sdwa v17, v17 dst_sel:DWORD dst_unused:UNUSED_PAD src0_sel:WORD_1
	v_cvt_f32_f16_sdwa v19, v33 dst_sel:DWORD dst_unused:UNUSED_PAD src0_sel:WORD_1
	v_mul_f32_e32 v15, v0, v15
	v_mul_f32_e32 v15, v15, v16
	v_mul_f32_e32 v16, v1, v17
	v_mul_f32_e32 v20, v16, v19
	v_med3_f32 v9, v9, s62, v187
	v_med3_f32 v14, v14, s62, v187
	v_mov_b32_e32 v19, v139
	v_cvt_pk_fp8_f32 v19, v9, v14
	v_med3_f32 v9, v15, s62, v187
	ds_read_b128 v[14:17], v48
	v_med3_f32 v20, v20, s62, v187
	v_cvt_pk_fp8_f32 v19, v9, v20 op_sel:[0,0,1]
	s_waitcnt vmcnt(5)
	v_cvt_f32_f16_e32 v22, v34
	v_cvt_f32_f16_sdwa v23, v34 dst_sel:DWORD dst_unused:UNUSED_PAD src0_sel:WORD_1
	s_waitcnt lgkmcnt(0)
	v_cvt_f32_f16_e32 v9, v14
	v_cvt_f32_f16_sdwa v14, v14 dst_sel:DWORD dst_unused:UNUSED_PAD src0_sel:WORD_1
	v_cvt_f32_f16_sdwa v24, v35 dst_sel:DWORD dst_unused:UNUSED_PAD src0_sel:WORD_1
	v_lshl_add_u64 v[20:21], s[30:31], 0, v[42:43]
	v_mul_f32_e32 v9, v6, v9
	v_mul_f32_e32 v9, v9, v22
	v_mul_f32_e32 v14, v7, v14
	v_cvt_f32_f16_e32 v22, v15
	v_mul_f32_e32 v14, v14, v23
	v_cvt_f32_f16_e32 v23, v35
	v_cvt_f32_f16_sdwa v15, v15 dst_sel:DWORD dst_unused:UNUSED_PAD src0_sel:WORD_1
	v_mul_f32_e32 v22, v4, v22
	v_med3_f32 v9, v9, s62, v187
	v_mul_f32_e32 v22, v22, v23
	v_med3_f32 v23, v14, s62, v187
	v_mov_b32_e32 v14, v139
	v_cvt_pk_fp8_f32 v14, v9, v23
	v_med3_f32 v9, v22, s62, v187
	v_cvt_f32_f16_e32 v22, v16
	v_cvt_f32_f16_sdwa v16, v16 dst_sel:DWORD dst_unused:UNUSED_PAD src0_sel:WORD_1
	v_mul_f32_e32 v15, v5, v15
	v_cvt_f32_f16_e32 v23, v36
	v_mul_f32_e32 v15, v15, v24
	v_med3_f32 v15, v15, s62, v187
	v_cvt_pk_fp8_f32 v14, v9, v15 op_sel:[0,0,1]
	v_mul_f32_e32 v9, v2, v22
	v_mul_f32_e32 v15, v3, v16
	v_cvt_f32_f16_sdwa v16, v36 dst_sel:DWORD dst_unused:UNUSED_PAD src0_sel:WORD_1
	v_cvt_f32_f16_e32 v22, v17
	v_mul_f32_e32 v9, v9, v23
	v_cvt_f32_f16_e32 v23, v37
	v_cvt_f32_f16_sdwa v17, v17 dst_sel:DWORD dst_unused:UNUSED_PAD src0_sel:WORD_1
	v_mul_f32_e32 v15, v15, v16
	v_mul_f32_e32 v16, v0, v22
	v_cvt_f32_f16_sdwa v22, v37 dst_sel:DWORD dst_unused:UNUSED_PAD src0_sel:WORD_1
	v_mul_f32_e32 v16, v16, v23
	v_med3_f32 v9, v9, s62, v187
	v_med3_f32 v23, v15, s62, v187
	v_mov_b32_e32 v15, v139
	v_cvt_pk_fp8_f32 v15, v9, v23
	v_mul_f32_e32 v17, v1, v17
	v_mul_f32_e32 v9, v17, v22
	v_med3_f32 v16, v16, s62, v187
	v_med3_f32 v9, v9, s62, v187
	v_cvt_pk_fp8_f32 v15, v16, v9 op_sel:[0,0,1]
	v_lshl_add_u64 v[20:21], v[20:21], 0, v[138:139]
	global_store_dwordx2 v[20:21], v[18:19], off offset:2048 nt
	v_add_u32_e32 v20, 16, v8
	v_ashrrev_i32_e32 v21, 31, v20
	global_store_dwordx2 v[12:13], v[14:15], off offset:2048 nt
	v_lshl_add_u64 v[12:13], v[64:65], 0, v[20:21]
	global_store_dwordx2 v[44:45], v[40:41], off offset:2048 nt
	v_lshlrev_b64 v[24:25], 12, v[12:13]
	v_lshl_add_u64 v[12:13], v[10:11], 0, v[24:25]
	v_add_u32_e32 v22, 20, v8
	v_ashrrev_i32_e32 v23, 31, v22
	v_lshl_add_u64 v[16:17], v[64:65], 0, v[22:23]
	v_lshlrev_b64 v[28:29], 12, v[16:17]
	v_lshl_add_u64 v[16:17], v[10:11], 0, v[28:29]
	v_lshl_add_u32 v9, v20, 8, v46
	v_add_u32_e32 v20, 24, v8
	v_ashrrev_i32_e32 v21, 31, v20
	v_lshl_add_u32 v36, v22, 8, v46
	v_lshl_add_u64 v[22:23], v[64:65], 0, v[20:21]
	v_lshlrev_b64 v[30:31], 12, v[22:23]
	v_lshl_add_u32 v37, v20, 8, v46
	ds_read_b128 v[20:23], v9
	v_add_u32_e32 v32, 28, v8
	v_ashrrev_i32_e32 v33, 31, v32
	v_lshl_add_u64 v[8:9], v[64:65], 0, v[32:33]
	v_lshlrev_b64 v[8:9], 12, v[8:9]
	v_lshl_add_u64 v[26:27], v[10:11], 0, v[30:31]
	v_lshl_add_u64 v[34:35], v[10:11], 0, v[8:9]
	s_waitcnt lgkmcnt(0)
	v_cvt_f32_f16_e32 v10, v20
	v_cvt_f32_f16_sdwa v20, v20 dst_sel:DWORD dst_unused:UNUSED_PAD src0_sel:WORD_1
	v_lshl_add_u32 v38, v32, 8, v46
	v_mov_b32_e32 v32, v139
	v_mul_f32_e32 v10, v6, v10
	v_mov_b32_e32 v33, v139
	s_waitcnt vmcnt(7)
	v_mov_b32_e32 v12, v236
	v_mov_b32_e32 v13, v237
	v_mov_b32_e32 v14, v238
	v_mov_b32_e32 v15, v239
	v_cvt_f32_f16_e32 v11, v12
	v_cvt_f32_f16_sdwa v12, v12 dst_sel:DWORD dst_unused:UNUSED_PAD src0_sel:WORD_1
	v_mul_f32_e32 v10, v10, v11
	v_mul_f32_e32 v11, v7, v20
	v_mul_f32_e32 v11, v11, v12
	v_cvt_f32_f16_e32 v12, v21
	v_cvt_f32_f16_e32 v20, v13
	v_cvt_f32_f16_sdwa v21, v21 dst_sel:DWORD dst_unused:UNUSED_PAD src0_sel:WORD_1
	v_cvt_f32_f16_sdwa v13, v13 dst_sel:DWORD dst_unused:UNUSED_PAD src0_sel:WORD_1
	v_mul_f32_e32 v12, v4, v12
	v_mul_f32_e32 v12, v12, v20
	v_mul_f32_e32 v20, v5, v21
	v_mul_f32_e32 v13, v20, v13
	v_med3_f32 v10, v10, s62, v187
	v_med3_f32 v11, v11, s62, v187
	v_cvt_pk_fp8_f32 v32, v10, v11
	v_med3_f32 v20, v12, s62, v187
	v_med3_f32 v21, v13, s62, v187
	v_cvt_pk_fp8_f32 v32, v20, v21 op_sel:[0,0,1]
	v_cvt_f32_f16_e32 v20, v22
	v_cvt_f32_f16_e32 v21, v14
	v_cvt_f32_f16_sdwa v22, v22 dst_sel:DWORD dst_unused:UNUSED_PAD src0_sel:WORD_1
	v_cvt_f32_f16_sdwa v14, v14 dst_sel:DWORD dst_unused:UNUSED_PAD src0_sel:WORD_1
	v_mul_f32_e32 v20, v2, v20
	v_mul_f32_e32 v20, v20, v21
	v_mul_f32_e32 v21, v3, v22
	v_mul_f32_e32 v14, v21, v14
	v_cvt_f32_f16_e32 v21, v23
	v_cvt_f32_f16_e32 v22, v15
	v_cvt_f32_f16_sdwa v23, v23 dst_sel:DWORD dst_unused:UNUSED_PAD src0_sel:WORD_1
	v_cvt_f32_f16_sdwa v15, v15 dst_sel:DWORD dst_unused:UNUSED_PAD src0_sel:WORD_1
	v_med3_f32 v20, v20, s62, v187
	v_med3_f32 v14, v14, s62, v187
	v_mul_f32_e32 v21, v0, v21
	v_cvt_pk_fp8_f32 v33, v20, v14
	v_mul_f32_e32 v21, v21, v22
	v_mul_f32_e32 v22, v1, v23
	v_mul_f32_e32 v15, v22, v15
	v_med3_f32 v14, v21, s62, v187
	v_med3_f32 v15, v15, s62, v187
	v_cvt_pk_fp8_f32 v33, v14, v15 op_sel:[0,0,1]
	v_lshl_add_u64 v[14:15], s[30:31], 0, v[24:25]
	ds_read_b128 v[20:23], v36
	v_lshl_add_u64 v[14:15], v[14:15], 0, v[138:139]
	s_waitcnt vmcnt(6)
	v_mov_b32_e32 v16, v240
	v_mov_b32_e32 v17, v241
	v_mov_b32_e32 v18, v242
	v_mov_b32_e32 v19, v243
	v_cvt_f32_f16_e32 v35, v16
	v_cvt_f32_f16_sdwa v16, v16 dst_sel:DWORD dst_unused:UNUSED_PAD src0_sel:WORD_1
	global_store_dwordx2 v[14:15], v[32:33], off offset:2048 nt
	s_waitcnt lgkmcnt(0)
	v_cvt_f32_f16_e32 v34, v20
	v_cvt_f32_f16_sdwa v20, v20 dst_sel:DWORD dst_unused:UNUSED_PAD src0_sel:WORD_1
	v_cvt_f32_f16_e32 v32, v17
	v_cvt_f32_f16_sdwa v17, v17 dst_sel:DWORD dst_unused:UNUSED_PAD src0_sel:WORD_1
	v_mul_f32_e32 v14, v6, v34
	v_mul_f32_e32 v15, v7, v20
	v_cvt_f32_f16_e32 v20, v21
	v_cvt_f32_f16_sdwa v21, v21 dst_sel:DWORD dst_unused:UNUSED_PAD src0_sel:WORD_1
	v_mul_f32_e32 v14, v14, v35
	v_mul_f32_e32 v15, v15, v16
	v_mul_f32_e32 v16, v4, v20
	v_med3_f32 v14, v14, s62, v187
	v_med3_f32 v15, v15, s62, v187
	v_mov_b32_e32 v20, v139
	v_cvt_pk_fp8_f32 v20, v14, v15
	v_mul_f32_e32 v21, v5, v21
	v_mul_f32_e32 v16, v16, v32
	v_mul_f32_e32 v14, v21, v17
	v_med3_f32 v15, v16, s62, v187
	v_med3_f32 v14, v14, s62, v187
	v_cvt_pk_fp8_f32 v20, v15, v14 op_sel:[0,0,1]
	v_cvt_f32_f16_e32 v14, v22
	v_cvt_f32_f16_e32 v15, v18
	v_cvt_f32_f16_sdwa v16, v22 dst_sel:DWORD dst_unused:UNUSED_PAD src0_sel:WORD_1
	v_cvt_f32_f16_sdwa v17, v18 dst_sel:DWORD dst_unused:UNUSED_PAD src0_sel:WORD_1
	v_mul_f32_e32 v14, v2, v14
	v_mul_f32_e32 v14, v14, v15
	v_mul_f32_e32 v15, v3, v16
	v_cvt_f32_f16_e32 v16, v23
	v_mul_f32_e32 v15, v15, v17
	v_cvt_f32_f16_e32 v17, v19
	v_cvt_f32_f16_sdwa v18, v23 dst_sel:DWORD dst_unused:UNUSED_PAD src0_sel:WORD_1
	v_cvt_f32_f16_sdwa v19, v19 dst_sel:DWORD dst_unused:UNUSED_PAD src0_sel:WORD_1
	v_med3_f32 v14, v14, s62, v187
	v_med3_f32 v15, v15, s62, v187
	v_mov_b32_e32 v21, v139
	v_mul_f32_e32 v16, v0, v16
	v_cvt_pk_fp8_f32 v21, v14, v15
	v_mul_f32_e32 v16, v16, v17
	v_mul_f32_e32 v17, v1, v18
	v_mul_f32_e32 v18, v17, v19
	v_med3_f32 v19, v16, s62, v187
	ds_read_b128 v[14:17], v37
	v_med3_f32 v18, v18, s62, v187
	v_cvt_pk_fp8_f32 v21, v19, v18 op_sel:[0,0,1]
	v_lshl_add_u64 v[18:19], s[30:31], 0, v[28:29]
	v_lshl_add_u64 v[18:19], v[18:19], 0, v[138:139]
	s_waitcnt lgkmcnt(0)
	v_cvt_f32_f16_e32 v22, v14
	v_cvt_f32_f16_sdwa v14, v14 dst_sel:DWORD dst_unused:UNUSED_PAD src0_sel:WORD_1
	s_waitcnt vmcnt(6)
	v_mov_b32_e32 v10, v244
	v_mov_b32_e32 v11, v245
	v_mov_b32_e32 v12, v246
	v_mov_b32_e32 v13, v247
	v_cvt_f32_f16_e32 v23, v10
	global_store_dwordx2 v[18:19], v[20:21], off offset:2048 nt
	v_cvt_f32_f16_sdwa v10, v10 dst_sel:DWORD dst_unused:UNUSED_PAD src0_sel:WORD_1
	v_cvt_f32_f16_e32 v19, v15
	v_cvt_f32_f16_e32 v20, v11
	v_mul_f32_e32 v18, v6, v22
	v_mul_f32_e32 v14, v7, v14
	v_cvt_f32_f16_sdwa v15, v15 dst_sel:DWORD dst_unused:UNUSED_PAD src0_sel:WORD_1
	v_mul_f32_e32 v18, v18, v23
	v_mul_f32_e32 v10, v14, v10
	v_mul_f32_e32 v14, v4, v19
	v_cvt_f32_f16_sdwa v11, v11 dst_sel:DWORD dst_unused:UNUSED_PAD src0_sel:WORD_1
	v_mul_f32_e32 v19, v14, v20
	v_med3_f32 v18, v18, s62, v187
	v_med3_f32 v10, v10, s62, v187
	v_mov_b32_e32 v14, v139
	v_cvt_pk_fp8_f32 v14, v18, v10
	v_mul_f32_e32 v15, v5, v15
	v_mul_f32_e32 v10, v15, v11
	v_med3_f32 v11, v19, s62, v187
	v_med3_f32 v10, v10, s62, v187
	v_cvt_pk_fp8_f32 v14, v11, v10 op_sel:[0,0,1]
	v_cvt_f32_f16_e32 v10, v16
	v_cvt_f32_f16_e32 v11, v12
	v_cvt_f32_f16_sdwa v15, v16 dst_sel:DWORD dst_unused:UNUSED_PAD src0_sel:WORD_1
	v_cvt_f32_f16_sdwa v12, v12 dst_sel:DWORD dst_unused:UNUSED_PAD src0_sel:WORD_1
	v_mul_f32_e32 v10, v2, v10
	v_mul_f32_e32 v10, v10, v11
	v_mul_f32_e32 v11, v3, v15
	v_mul_f32_e32 v11, v11, v12
	v_cvt_f32_f16_e32 v12, v17
	v_cvt_f32_f16_e32 v15, v13
	v_cvt_f32_f16_sdwa v16, v17 dst_sel:DWORD dst_unused:UNUSED_PAD src0_sel:WORD_1
	v_cvt_f32_f16_sdwa v13, v13 dst_sel:DWORD dst_unused:UNUSED_PAD src0_sel:WORD_1
	v_mul_f32_e32 v12, v0, v12
	v_mul_f32_e32 v12, v12, v15
	v_mul_f32_e32 v15, v1, v16
	v_mul_f32_e32 v16, v15, v13
	v_med3_f32 v10, v10, s62, v187
	v_med3_f32 v11, v11, s62, v187
	v_mov_b32_e32 v15, v139
	v_cvt_pk_fp8_f32 v15, v10, v11
	v_med3_f32 v17, v12, s62, v187
	ds_read_b128 v[10:13], v38
	s_waitcnt vmcnt(6)
	v_mov_b32_e32 v24, v248
	v_mov_b32_e32 v25, v249
	v_mov_b32_e32 v26, v250
	v_mov_b32_e32 v27, v251
	v_cvt_f32_f16_e32 v19, v24
	v_cvt_f32_f16_sdwa v20, v24 dst_sel:DWORD dst_unused:UNUSED_PAD src0_sel:WORD_1
	v_med3_f32 v16, v16, s62, v187
	v_cvt_pk_fp8_f32 v15, v17, v16 op_sel:[0,0,1]
	s_waitcnt lgkmcnt(0)
	v_cvt_f32_f16_e32 v18, v10
	v_cvt_f32_f16_sdwa v10, v10 dst_sel:DWORD dst_unused:UNUSED_PAD src0_sel:WORD_1
	v_lshl_add_u64 v[16:17], s[30:31], 0, v[30:31]
	v_lshl_add_u64 v[16:17], v[16:17], 0, v[138:139]
	v_mul_f32_e32 v6, v6, v18
	v_mul_f32_e32 v7, v7, v10
	v_cvt_f32_f16_e32 v10, v11
	v_cvt_f32_f16_e32 v18, v25
	v_cvt_f32_f16_sdwa v11, v11 dst_sel:DWORD dst_unused:UNUSED_PAD src0_sel:WORD_1
	v_mul_f32_e32 v6, v6, v19
	v_cvt_f32_f16_sdwa v19, v25 dst_sel:DWORD dst_unused:UNUSED_PAD src0_sel:WORD_1
	v_mul_f32_e32 v4, v4, v10
	v_mul_f32_e32 v7, v7, v20
	v_mul_f32_e32 v10, v4, v18
	v_mul_f32_e32 v4, v5, v11
	v_mul_f32_e32 v5, v4, v19
	v_med3_f32 v6, v6, s62, v187
	v_med3_f32 v7, v7, s62, v187
	v_mov_b32_e32 v4, v139
	v_cvt_pk_fp8_f32 v4, v6, v7
	v_cvt_f32_f16_e32 v7, v12
	v_med3_f32 v6, v10, s62, v187
	v_med3_f32 v5, v5, s62, v187
	v_cvt_f32_f16_e32 v10, v26
	v_cvt_f32_f16_sdwa v11, v12 dst_sel:DWORD dst_unused:UNUSED_PAD src0_sel:WORD_1
	v_cvt_pk_fp8_f32 v4, v6, v5 op_sel:[0,0,1]
	v_cvt_f32_f16_sdwa v5, v26 dst_sel:DWORD dst_unused:UNUSED_PAD src0_sel:WORD_1
	v_cvt_f32_f16_e32 v6, v13
	v_mul_f32_e32 v2, v2, v7
	v_mul_f32_e32 v2, v2, v10
	v_mul_f32_e32 v3, v3, v11
	v_cvt_f32_f16_sdwa v10, v13 dst_sel:DWORD dst_unused:UNUSED_PAD src0_sel:WORD_1
	v_cvt_f32_f16_e32 v7, v27
	v_mul_f32_e32 v3, v3, v5
	v_mul_f32_e32 v0, v0, v6
	v_cvt_f32_f16_sdwa v6, v27 dst_sel:DWORD dst_unused:UNUSED_PAD src0_sel:WORD_1
	v_med3_f32 v2, v2, s62, v187
	v_med3_f32 v3, v3, s62, v187
	v_mov_b32_e32 v5, v139
	v_cvt_pk_fp8_f32 v5, v2, v3
	v_mul_f32_e32 v1, v1, v10
	v_mul_f32_e32 v0, v0, v7
	v_mul_f32_e32 v1, v1, v6
	v_med3_f32 v0, v0, s62, v187
	v_med3_f32 v1, v1, s62, v187
	v_cvt_pk_fp8_f32 v5, v0, v1 op_sel:[0,0,1]
	v_lshl_add_u64 v[0:1], s[30:31], 0, v[8:9]
	v_lshl_add_u64 v[0:1], v[0:1], 0, v[138:139]
	global_store_dwordx2 v[16:17], v[14:15], off offset:2048 nt
	global_store_dwordx2 v[0:1], v[4:5], off offset:2048 nt
	s_cbranch_vccnz .LBB0_1610
